# RET chain step top waits vmcnt(2) so the two O stores of the previous step stay in flight (first step still drains)
# speedup vs baseline: 1.0042x; 1.0042x over previous
; #define LAS __attribute__((address_space(3)))
; DI void ret_chain_phase(const Ctx& a, LAS unsigned char* lds) {
;     ...
;         for (int s = 0; s < 68; ++s) {
;             const int row0 = RC_ROW0(s);
; #pragma unroll
;             for (int k = 0; k < 4; ++k) { const int p = tid + k * NTHREADS; const int d = p >> 3, ch = p & 7;
;                 *(LAS u32x4*)(lds + RC_SKT + d * 128 + ((ch ^ ((d >> 1) & 7)) << 4)) = pkt[k]; }
;             { const int v_ = tid >> 3, ch = tid & 7;
;                 *(LAS u32x4*)(lds + RC_SVT + v_ * 128 + ((ch ^ ((v_ >> 1) & 7)) << 4)) = pvt; }
;             asm volatile("s_waitcnt vmcnt(0)" ::: "memory");
;             if (s + 1 < 68) RC_ISSUE(s + 1);
.LBB0_203:
	s_cmp_eq_u32 s45, 0
	s_cbranch_scc1 .Lrc_top_first
	s_waitcnt vmcnt(2)
	s_branch .Lrc_top_go

; #define LAS __attribute__((address_space(3)))
; DI void ret_chain_phase(const Ctx& a, LAS unsigned char* lds) {
;     ...
;             for (int k = 0; k < 4; ++k) { const int p = tid + k * NTHREADS; const int d = p >> 3, ch = p & 7;
;                 *(LAS u32x4*)(lds + RC_SKT + d * 128 + ((ch ^ ((d >> 1) & 7)) << 4)) = pkt[k]; }
;             { const int v_ = tid >> 3, ch = tid & 7;
;                 *(LAS u32x4*)(lds + RC_SVT + v_ * 128 + ((ch ^ ((v_ >> 1) & 7)) << 4)) = pvt; }
;             asm volatile("s_waitcnt vmcnt(0)" ::: "memory");
;             if (s + 1 < 68) RC_ISSUE(s + 1);
.Lrc_top_go:
	ds_write_b128 v173, v[32:35]
	ds_write_b128 v173, v[36:39] offset:8192
	ds_write_b128 v173, v[40:43] offset:16384
	ds_write_b128 v173, v[44:47] offset:24576
	ds_write_b128 v174, v[48:51]
	s_cmp_gt_u32 s45, 2
	s_cselect_b64 s[30:31], -1, 0
	s_mov_b64 s[46:47], -1
	s_and_b64 vcc, exec, s[30:31]
	s_cbranch_vccz .LBB0_205
	s_add_i32 s26, s45, -3
	s_and_b64 s[20:21], s[42:43], exec
	s_cselect_b32 s51, s26, s48
	s_mov_b64 s[46:47], 0
